# S1 chunk-state phase: 16 xbc staging loads per thread issued up front and overlapped with the dt scan (was load-wait-write x16)
# speedup vs baseline: 1.0118x; 1.0061x over previous
.LBB0_296:
	v_ashrrev_i32_e32 v14, 6, v86
	v_add_u32_e32 v12, s2, v14
	s_movk_i32 s18, 0x600
	v_mad_i64_i32 v[12:13], s[18:19], v12, s18, v[82:83]
	s_mov_b32 s36, 0x3000
	s_mov_b32 s37, 0
	global_load_dwordx4 v[120:123], v[12:13], off
	v_lshl_add_u64 v[12:13], v[12:13], 0, s[36:37]
	global_load_dwordx4 v[124:127], v[12:13], off
	v_lshl_add_u64 v[12:13], v[12:13], 0, s[36:37]
	global_load_dwordx4 v[130:133], v[12:13], off
	v_lshl_add_u64 v[12:13], v[12:13], 0, s[36:37]
	global_load_dwordx4 v[138:141], v[12:13], off
	v_lshl_add_u64 v[12:13], v[12:13], 0, s[36:37]
	global_load_dwordx4 v[142:145], v[12:13], off
	v_lshl_add_u64 v[12:13], v[12:13], 0, s[36:37]
	global_load_dwordx4 v[146:149], v[12:13], off
	v_lshl_add_u64 v[12:13], v[12:13], 0, s[36:37]
	global_load_dwordx4 v[150:153], v[12:13], off
	v_lshl_add_u64 v[12:13], v[12:13], 0, s[36:37]
	global_load_dwordx4 v[156:159], v[12:13], off
	v_lshl_add_u64 v[12:13], v[12:13], 0, s[36:37]
	global_load_dwordx4 v[166:169], v[12:13], off
	v_lshl_add_u64 v[12:13], v[12:13], 0, s[36:37]
	global_load_dwordx4 v[170:173], v[12:13], off
	v_lshl_add_u64 v[12:13], v[12:13], 0, s[36:37]
	global_load_dwordx4 v[174:177], v[12:13], off
	v_lshl_add_u64 v[12:13], v[12:13], 0, s[36:37]
	global_load_dwordx4 v[178:181], v[12:13], off
	v_lshl_add_u64 v[12:13], v[12:13], 0, s[36:37]
	global_load_dwordx4 v[182:185], v[12:13], off
	v_lshl_add_u64 v[12:13], v[12:13], 0, s[36:37]
	global_load_dwordx4 v[186:189], v[12:13], off
	v_lshl_add_u64 v[12:13], v[12:13], 0, s[36:37]
	global_load_dwordx4 v[204:207], v[12:13], off
	v_lshl_add_u64 v[12:13], v[12:13], 0, s[36:37]
	global_load_dwordx4 v[208:211], v[12:13], off
	v_mul_u32_u24_e32 v14, 0x220, v14
	v_add_u32_e32 v15, 0xfffffe00, v100
	v_cndmask_b32_e64 v15, v101, v15, s[52:53]
	v_add_u32_e32 v14, v14, v15
	v_add_u32_e32 v0, s2, v88
	v_ashrrev_i32_e32 v1, 31, v0
	v_lshl_add_u64 v[0:1], v[0:1], 3, s[0:1]
	v_readlane_b32 s4, v251, 45
	v_lshlrev_b64 v[2:3], 2, v[0:1]
	v_readlane_b32 s5, v251, 46
	s_nop 1
	v_lshl_add_u64 v[0:1], s[4:5], 0, v[2:3]
	global_load_dword v6, v[0:1], off
	v_add_u32_e32 v0, s2, v89
	v_ashrrev_i32_e32 v1, 31, v0
	v_lshl_add_u64 v[0:1], v[0:1], 3, s[0:1]
	v_lshlrev_b64 v[4:5], 2, v[0:1]
	v_lshl_add_u64 v[0:1], s[4:5], 0, v[4:5]
	global_load_dword v1, v[0:1], off
	v_readlane_b32 s4, v251, 47
	v_readlane_b32 s5, v251, 48
	s_waitcnt vmcnt(0)
	v_mul_f32_e32 v0, v87, v1
	v_fma_f32 v0, v6, -v87, -v0
	ds_bpermute_b32 v7, v94, v0
	v_lshl_add_u64 v[2:3], s[4:5], 0, v[2:3]
	s_waitcnt lgkmcnt(0)
	v_add_f32_e32 v7, v0, v7
	v_cndmask_b32_e64 v7, v7, v0, s[38:39]
	ds_bpermute_b32 v10, v95, v7
	s_waitcnt lgkmcnt(0)
	v_add_f32_e32 v10, v7, v10
	v_cndmask_b32_e64 v7, v10, v7, s[42:43]
	ds_bpermute_b32 v10, v96, v7
	s_waitcnt lgkmcnt(0)
	v_add_f32_e32 v10, v7, v10
	v_cndmask_b32_e64 v7, v10, v7, s[44:45]
	ds_bpermute_b32 v10, v97, v7
	s_waitcnt lgkmcnt(0)
	v_add_f32_e32 v10, v7, v10
	v_cndmask_b32_e64 v7, v10, v7, s[46:47]
	ds_bpermute_b32 v10, v98, v7
	s_waitcnt lgkmcnt(0)
	v_add_f32_e32 v10, v7, v10
	v_cndmask_b32_e64 v7, v10, v7, s[48:49]
	ds_bpermute_b32 v10, v99, v7
	s_waitcnt lgkmcnt(0)
	v_add_f32_e32 v10, v7, v10
	v_cndmask_b32_e64 v7, v10, v7, s[50:51]
	v_sub_f32_e32 v10, v7, v0
	v_fma_f32 v11, v6, -v87, v10
	v_add_f32_e32 v10, v0, v10
	ds_bpermute_b32 v0, v90, v7
	global_store_dword v[2:3], v11, off
	v_lshl_add_u64 v[2:3], s[4:5], 0, v[4:5]
	global_store_dword v[2:3], v10, off
	s_waitcnt lgkmcnt(0)
	v_sub_f32_e32 v2, v0, v11
	v_mul_f32_e32 v2, 0x3fb8aa3b, v2
	v_exp_f32_e32 v2, v2
	s_nop 0
	v_mul_f32_e32 v2, v6, v2
	ds_write_b32 v91, v2
	v_sub_f32_e32 v2, v0, v10
	v_mul_f32_e32 v2, 0x3fb8aa3b, v2
	v_exp_f32_e32 v2, v2
	s_nop 0
	v_mul_f32_e32 v1, v1, v2
	ds_write_b32 v92, v1
	s_and_saveexec_b64 s[4:5], s[38:39]
	s_cbranch_execz .LBB0_298
	s_lshl_b32 s3, s26, 3
	v_mul_f32_e32 v0, 0x3fb8aa3b, v0
	s_add_i32 s6, s3, s24
	v_exp_f32_e32 v0, v0
	s_ashr_i32 s7, s6, 31
	s_lshl_b64 s[6:7], s[6:7], 2
	v_readlane_b32 s18, v251, 55
	v_readlane_b32 s19, v251, 56
	s_add_u32 s6, s18, s6
	s_addc_u32 s7, s19, s7
	global_store_dword v9, v0, s[6:7]
.LBB0_298:
	s_or_b64 exec, exec, s[4:5]
	s_and_saveexec_b64 s[4:5], s[40:41]
	s_movk_i32 s3, 0x1dff
	s_cbranch_execz .LBB0_305
	s_waitcnt vmcnt(0)
	ds_write_b128 v14, v[120:123]
	ds_write_b128 v14, v[124:127] offset:4352
	ds_write_b128 v14, v[130:133] offset:8704
	ds_write_b128 v14, v[138:141] offset:13056
	ds_write_b128 v14, v[142:145] offset:17408
	ds_write_b128 v14, v[146:149] offset:21760
	ds_write_b128 v14, v[150:153] offset:26112
	ds_write_b128 v14, v[156:159] offset:30464
	ds_write_b128 v14, v[166:169] offset:34816
	ds_write_b128 v14, v[170:173] offset:39168
	ds_write_b128 v14, v[174:177] offset:43520
	ds_write_b128 v14, v[178:181] offset:47872
	ds_write_b128 v14, v[182:185] offset:52224
	ds_write_b128 v14, v[186:189] offset:56576
	ds_write_b128 v14, v[204:207] offset:60928
	ds_write_b128 v14, v[208:211] offset:65280
